# prompt attention: packed v_pk_mul_f32 (P x 1/sum, feeding the PV MFMA operands) split into scalar v_mul_f32 pairs (31 sites, bit-identical)
# baseline (speedup 1.0000x reference)
.LBB0_124:
	s_waitcnt vmcnt(1)
	v_mov_b64_e32 v[16:17], v[4:5]
	v_mov_b32_e32 v36, v22
	v_mov_b64_e32 v[14:15], v[2:3]
	global_load_dwordx4 v[2:5], v[32:33], off offset:-64
	global_load_dwordx4 v[6:9], v[32:33], off
	s_load_dwordx2 s[48:49], s[80:81], 0xd0
	v_cndmask_b32_e64 v41, v195, v36, s[38:39]
	v_add_u32_e32 v46, 0x80, v36
	v_lshl_add_u64 v[32:33], v[32:33], 0, s[94:95]
	s_waitcnt lgkmcnt(0)
	s_add_u32 s2, s48, s46
	s_addc_u32 s3, s49, s47
	global_load_dword v40, v1, s[2:3]
	s_add_i32 s2, s28, 0
	s_add_i32 s2, s2, 0x11400
	s_addk_i32 s28, 0x200
	s_add_u32 s46, s46, 4
	s_addc_u32 s47, s47, 0
	s_cmpk_eq_i32 s28, 0xe00
	ds_read_b128 v[214:217], v78
	ds_read_b128 v[218:221], v78 offset:64
	v_bfi_b32 v206, v205, v79, s2
	ds_read_b32 v206, v206
	v_bfi_b32 v207, v205, v80, s2
	ds_read_b32 v207, v207
	v_bfi_b32 v208, v205, v81, s2
	ds_read_b32 v208, v208
	v_bfi_b32 v209, v205, v82, s2
	ds_read_b32 v209, v209
	ds_read_b128 v[222:225], v83
	ds_read_b128 v[226:229], v83 offset:64
	s_waitcnt vmcnt(3) lgkmcnt(6)
	v_mfma_f32_16x16x32_bf16 v[230:233], v[214:217], v[14:17], 0
	v_mfma_f32_16x16x32_bf16 v[230:233], v[218:221], v[10:13], v[230:233]
	v_ashrrev_i32_e32 v210, 31, v79
	v_and_b32_e32 v210, 0xff800000, v210
	v_ashrrev_i32_e32 v211, 31, v80
	v_and_b32_e32 v211, 0xff800000, v211
	v_ashrrev_i32_e32 v212, 31, v81
	v_and_b32_e32 v212, 0xff800000, v212
	v_ashrrev_i32_e32 v213, 31, v82
	v_and_b32_e32 v213, 0xff800000, v213
	s_nop 1
	s_waitcnt lgkmcnt(2)
	v_add_f32_e32 v234, v230, v206
	v_add_f32_e32 v47, v234, v210
	v_add_f32_e32 v234, v231, v207
	v_add_f32_e32 v48, v234, v211
	v_add_f32_e32 v234, v232, v208
	v_add_f32_e32 v49, v234, v212
	v_add_f32_e32 v234, v233, v209
	v_add_f32_e32 v50, v234, v213
	v_max3_f32 v36, v47, s96, v48
	v_max3_f32 v51, v36, v49, v50
	v_bfi_b32 v206, v205, v84, s2
	ds_read_b32 v206, v206
	v_bfi_b32 v207, v205, v85, s2
	ds_read_b32 v207, v207
	v_bfi_b32 v208, v205, v86, s2
	ds_read_b32 v208, v208
	v_bfi_b32 v209, v205, v87, s2
	ds_read_b32 v209, v209
	ds_read_b128 v[214:217], v88
	ds_read_b128 v[218:221], v88 offset:64
	s_waitcnt lgkmcnt(6)
	v_mfma_f32_16x16x32_bf16 v[230:233], v[222:225], v[14:17], 0
	v_mfma_f32_16x16x32_bf16 v[230:233], v[226:229], v[10:13], v[230:233]
	v_ashrrev_i32_e32 v210, 31, v84
	v_and_b32_e32 v210, 0xff800000, v210
	v_ashrrev_i32_e32 v211, 31, v85
	v_and_b32_e32 v211, 0xff800000, v211
	v_ashrrev_i32_e32 v212, 31, v86
	v_and_b32_e32 v212, 0xff800000, v212
	v_ashrrev_i32_e32 v213, 31, v87
	v_and_b32_e32 v213, 0xff800000, v213
	s_nop 1
	s_waitcnt lgkmcnt(2)
	v_add_f32_e32 v234, v230, v206
	v_add_f32_e32 v52, v234, v210
	v_add_f32_e32 v234, v231, v207
	v_add_f32_e32 v53, v234, v211
	v_add_f32_e32 v234, v232, v208
	v_add_f32_e32 v51, v234, v212
	v_add_f32_e32 v234, v233, v209
	v_add_f32_e32 v54, v234, v213
	v_max3_f32 v36, v51, v52, v53
	v_max3_f32 v55, v36, v51, v54
	v_bfi_b32 v206, v205, v89, s2
	ds_read_b32 v206, v206
	v_bfi_b32 v207, v205, v90, s2
	ds_read_b32 v207, v207
	v_bfi_b32 v208, v205, v91, s2
	ds_read_b32 v208, v208
	v_bfi_b32 v209, v205, v92, s2
	ds_read_b32 v209, v209
	ds_read_b128 v[222:225], v93
	ds_read_b128 v[226:229], v93 offset:64
	s_waitcnt lgkmcnt(6)
	v_mfma_f32_16x16x32_bf16 v[230:233], v[214:217], v[14:17], 0
	v_mfma_f32_16x16x32_bf16 v[230:233], v[218:221], v[10:13], v[230:233]
	v_ashrrev_i32_e32 v210, 31, v89
	v_and_b32_e32 v210, 0xff800000, v210
	v_ashrrev_i32_e32 v211, 31, v90
	v_and_b32_e32 v211, 0xff800000, v211
	v_ashrrev_i32_e32 v212, 31, v91
	v_and_b32_e32 v212, 0xff800000, v212
	v_ashrrev_i32_e32 v213, 31, v92
	v_and_b32_e32 v213, 0xff800000, v213
	s_nop 1
	s_waitcnt lgkmcnt(2)
	v_add_f32_e32 v234, v230, v206
	v_add_f32_e32 v56, v234, v210
	v_add_f32_e32 v234, v231, v207
	v_add_f32_e32 v57, v234, v211
	v_add_f32_e32 v234, v232, v208
	v_add_f32_e32 v55, v234, v212
	v_add_f32_e32 v234, v233, v209
	v_add_f32_e32 v61, v234, v213
	v_max3_f32 v36, v55, v56, v57
	v_max3_f32 v58, v36, v55, v61
	v_bfi_b32 v206, v205, v94, s2
	ds_read_b32 v206, v206
	v_bfi_b32 v207, v205, v95, s2
	ds_read_b32 v207, v207
	v_bfi_b32 v208, v205, v96, s2
	ds_read_b32 v208, v208
	v_bfi_b32 v209, v205, v97, s2
	ds_read_b32 v209, v209
	ds_read_b128 v[214:217], v98
	ds_read_b128 v[218:221], v98 offset:64
	s_waitcnt lgkmcnt(6)
	v_mfma_f32_16x16x32_bf16 v[230:233], v[222:225], v[14:17], 0
	v_mfma_f32_16x16x32_bf16 v[230:233], v[226:229], v[10:13], v[230:233]
	v_ashrrev_i32_e32 v210, 31, v94
	v_and_b32_e32 v210, 0xff800000, v210
	v_ashrrev_i32_e32 v211, 31, v95
	v_and_b32_e32 v211, 0xff800000, v211
	v_ashrrev_i32_e32 v212, 31, v96
	v_and_b32_e32 v212, 0xff800000, v212
	v_ashrrev_i32_e32 v213, 31, v97
	v_and_b32_e32 v213, 0xff800000, v213
	s_nop 1
	s_waitcnt lgkmcnt(2)
	v_add_f32_e32 v234, v230, v206
	v_add_f32_e32 v62, v234, v210
	v_add_f32_e32 v234, v231, v207
	v_add_f32_e32 v63, v234, v211
	v_add_f32_e32 v234, v232, v208
	v_add_f32_e32 v64, v234, v212
	v_add_f32_e32 v234, v233, v209
	v_add_f32_e32 v65, v234, v213
	v_max3_f32 v36, v58, v62, v63
	v_max3_f32 v58, v36, v64, v65
	v_bfi_b32 v206, v205, v99, s2
	ds_read_b32 v206, v206
	v_bfi_b32 v207, v205, v100, s2
	ds_read_b32 v207, v207
	v_bfi_b32 v208, v205, v101, s2
	ds_read_b32 v208, v208
	v_bfi_b32 v209, v205, v102, s2
	ds_read_b32 v209, v209
	ds_read_b128 v[222:225], v103
	ds_read_b128 v[226:229], v103 offset:64
	s_waitcnt lgkmcnt(6)
	v_mfma_f32_16x16x32_bf16 v[230:233], v[214:217], v[14:17], 0
	v_mfma_f32_16x16x32_bf16 v[230:233], v[218:221], v[10:13], v[230:233]
	v_ashrrev_i32_e32 v210, 31, v99
	v_and_b32_e32 v210, 0xff800000, v210
	v_ashrrev_i32_e32 v211, 31, v100
	v_and_b32_e32 v211, 0xff800000, v211
	v_ashrrev_i32_e32 v212, 31, v101
	v_and_b32_e32 v212, 0xff800000, v212
	v_ashrrev_i32_e32 v213, 31, v102
	v_and_b32_e32 v213, 0xff800000, v213
	s_nop 1
	s_waitcnt lgkmcnt(2)
	v_add_f32_e32 v234, v230, v206
	v_add_f32_e32 v137, v234, v210
	v_add_f32_e32 v234, v231, v207
	v_add_f32_e32 v142, v234, v211
	v_add_f32_e32 v234, v232, v208
	v_add_f32_e32 v143, v234, v212
	v_add_f32_e32 v234, v233, v209
	v_add_f32_e32 v144, v234, v213
	v_max3_f32 v36, v58, v137, v142
	v_max3_f32 v58, v36, v143, v144
	v_bfi_b32 v206, v205, v104, s2
	ds_read_b32 v206, v206
	v_bfi_b32 v207, v205, v105, s2
	ds_read_b32 v207, v207
	v_bfi_b32 v208, v205, v106, s2
	ds_read_b32 v208, v208
	v_bfi_b32 v209, v205, v107, s2
	ds_read_b32 v209, v209
	ds_read_b128 v[214:217], v108
	ds_read_b128 v[218:221], v108 offset:64
	s_waitcnt lgkmcnt(6)
	v_mfma_f32_16x16x32_bf16 v[230:233], v[222:225], v[14:17], 0
	v_mfma_f32_16x16x32_bf16 v[230:233], v[226:229], v[10:13], v[230:233]
	v_ashrrev_i32_e32 v210, 31, v104
	v_and_b32_e32 v210, 0xff800000, v210
	v_ashrrev_i32_e32 v211, 31, v105
	v_and_b32_e32 v211, 0xff800000, v211
	v_ashrrev_i32_e32 v212, 31, v106
	v_and_b32_e32 v212, 0xff800000, v212
	v_ashrrev_i32_e32 v213, 31, v107
	v_and_b32_e32 v213, 0xff800000, v213
	s_nop 1
	s_waitcnt lgkmcnt(2)
	v_add_f32_e32 v234, v230, v206
	v_add_f32_e32 v145, v234, v210
	v_add_f32_e32 v234, v231, v207
	v_add_f32_e32 v162, v234, v211
	v_add_f32_e32 v234, v232, v208
	v_add_f32_e32 v163, v234, v212
	v_add_f32_e32 v234, v233, v209
	v_add_f32_e32 v164, v234, v213
	v_max3_f32 v36, v58, v145, v162
	v_max3_f32 v58, v36, v163, v164
	v_bfi_b32 v206, v205, v109, s2
	ds_read_b32 v206, v206
	v_bfi_b32 v207, v205, v110, s2
	ds_read_b32 v207, v207
	v_bfi_b32 v208, v205, v111, s2
	ds_read_b32 v208, v208
	v_bfi_b32 v209, v205, v112, s2
	ds_read_b32 v209, v209
	ds_read_b128 v[222:225], v113
	ds_read_b128 v[226:229], v113 offset:64
	s_waitcnt lgkmcnt(6)
	v_mfma_f32_16x16x32_bf16 v[230:233], v[214:217], v[14:17], 0
	v_mfma_f32_16x16x32_bf16 v[230:233], v[218:221], v[10:13], v[230:233]
	v_ashrrev_i32_e32 v210, 31, v109
	v_and_b32_e32 v210, 0xff800000, v210
	v_ashrrev_i32_e32 v211, 31, v110
	v_and_b32_e32 v211, 0xff800000, v211
	v_ashrrev_i32_e32 v212, 31, v111
	v_and_b32_e32 v212, 0xff800000, v212
	v_ashrrev_i32_e32 v213, 31, v112
	v_and_b32_e32 v213, 0xff800000, v213
	s_nop 1
	s_waitcnt lgkmcnt(2)
	v_add_f32_e32 v234, v230, v206
	v_add_f32_e32 v165, v234, v210
	v_add_f32_e32 v234, v231, v207
	v_add_f32_e32 v166, v234, v211
	v_add_f32_e32 v234, v232, v208
	v_add_f32_e32 v167, v234, v212
	v_add_f32_e32 v234, v233, v209
	v_add_f32_e32 v168, v234, v213
	v_max3_f32 v36, v58, v165, v166
	v_max3_f32 v58, v36, v167, v168
	v_bfi_b32 v206, v205, v114, s2
	ds_read_b32 v206, v206
	v_bfi_b32 v207, v205, v115, s2
	ds_read_b32 v207, v207
	v_bfi_b32 v208, v205, v116, s2
	ds_read_b32 v208, v208
	v_bfi_b32 v209, v205, v117, s2
	ds_read_b32 v209, v209
	ds_read_b128 v[214:217], v118
	ds_read_b128 v[218:221], v118 offset:64
	s_waitcnt lgkmcnt(6)
	v_mfma_f32_16x16x32_bf16 v[230:233], v[222:225], v[14:17], 0
	v_mfma_f32_16x16x32_bf16 v[230:233], v[226:229], v[10:13], v[230:233]
	v_ashrrev_i32_e32 v210, 31, v114
	v_and_b32_e32 v210, 0xff800000, v210
	v_ashrrev_i32_e32 v211, 31, v115
	v_and_b32_e32 v211, 0xff800000, v211
	v_ashrrev_i32_e32 v212, 31, v116
	v_and_b32_e32 v212, 0xff800000, v212
	v_ashrrev_i32_e32 v213, 31, v117
	v_and_b32_e32 v213, 0xff800000, v213
	s_nop 1
	s_waitcnt lgkmcnt(2)
	v_add_f32_e32 v234, v230, v206
	v_add_f32_e32 v169, v234, v210
	v_add_f32_e32 v234, v231, v207
	v_add_f32_e32 v170, v234, v211
	v_add_f32_e32 v234, v232, v208
	v_add_f32_e32 v171, v234, v212
	v_add_f32_e32 v234, v233, v209
	v_add_f32_e32 v172, v234, v213
	v_max3_f32 v36, v58, v169, v170
	v_max3_f32 v58, v36, v171, v172
	v_bfi_b32 v206, v205, v119, s2
	ds_read_b32 v206, v206
	v_bfi_b32 v207, v205, v120, s2
	ds_read_b32 v207, v207
	v_bfi_b32 v208, v205, v121, s2
	ds_read_b32 v208, v208
	v_bfi_b32 v209, v205, v122, s2
	ds_read_b32 v209, v209
	ds_read_b128 v[222:225], v123
	ds_read_b128 v[226:229], v123 offset:64
	s_waitcnt lgkmcnt(6)
	v_mfma_f32_16x16x32_bf16 v[230:233], v[214:217], v[14:17], 0
	v_mfma_f32_16x16x32_bf16 v[230:233], v[218:221], v[10:13], v[230:233]
	v_ashrrev_i32_e32 v210, 31, v119
	v_and_b32_e32 v210, 0xff800000, v210
	v_ashrrev_i32_e32 v211, 31, v120
	v_and_b32_e32 v211, 0xff800000, v211
	v_ashrrev_i32_e32 v212, 31, v121
	v_and_b32_e32 v212, 0xff800000, v212
	v_ashrrev_i32_e32 v213, 31, v122
	v_and_b32_e32 v213, 0xff800000, v213
	s_nop 1
	s_waitcnt lgkmcnt(2)
	v_add_f32_e32 v234, v230, v206
	v_add_f32_e32 v173, v234, v210
	v_add_f32_e32 v234, v231, v207
	v_add_f32_e32 v174, v234, v211
	v_add_f32_e32 v234, v232, v208
	v_add_f32_e32 v175, v234, v212
	v_add_f32_e32 v234, v233, v209
	v_add_f32_e32 v176, v234, v213
	v_max3_f32 v36, v58, v173, v174
	v_max3_f32 v58, v36, v175, v176
	v_bfi_b32 v206, v205, v124, s2
	ds_read_b32 v206, v206
	v_bfi_b32 v207, v205, v125, s2
	ds_read_b32 v207, v207
	v_bfi_b32 v208, v205, v126, s2
	ds_read_b32 v208, v208
	v_bfi_b32 v209, v205, v127, s2
	ds_read_b32 v209, v209
	s_waitcnt lgkmcnt(4)
	v_mfma_f32_16x16x32_bf16 v[230:233], v[222:225], v[14:17], 0
	v_mfma_f32_16x16x32_bf16 v[230:233], v[226:229], v[10:13], v[230:233]
	v_ashrrev_i32_e32 v210, 31, v124
	v_and_b32_e32 v210, 0xff800000, v210
	v_ashrrev_i32_e32 v211, 31, v125
	v_and_b32_e32 v211, 0xff800000, v211
	v_ashrrev_i32_e32 v212, 31, v126
	v_and_b32_e32 v212, 0xff800000, v212
	v_ashrrev_i32_e32 v213, 31, v127
	v_and_b32_e32 v213, 0xff800000, v213
	s_nop 1
	s_waitcnt lgkmcnt(0)
	v_add_f32_e32 v234, v230, v206
	v_add_f32_e32 v36, v234, v210
	v_add_f32_e32 v234, v231, v207
	v_add_f32_e32 v37, v234, v211
	v_add_f32_e32 v234, v232, v208
	v_add_f32_e32 v38, v234, v212
	v_add_f32_e32 v234, v233, v209
	v_add_f32_e32 v39, v234, v213
	v_max3_f32 v10, v58, v36, v37
	v_max3_f32 v10, v10, v38, v39
	ds_swizzle_b32 v11, v10 offset:swizzle(SWAP,16)
	s_waitcnt lgkmcnt(0)
	v_max_f32_e32 v11, v11, v11
	v_max_f32_e32 v10, v10, v11
	ds_bpermute_b32 v11, v19, v10
	s_waitcnt vmcnt(0) lgkmcnt(0)
	v_max3_f32 v41, v10, v11, v40
	v_sub_f32_e32 v15, v52, v41
	v_mul_f32_e32 v15, 0x3fb8aa3b, v15
	v_exp_f32_e32 v138, v15
	v_sub_f32_e32 v15, v53, v41
	v_mul_f32_e32 v15, 0x3fb8aa3b, v15
	v_exp_f32_e32 v139, v15
	v_sub_f32_e32 v15, v51, v41
	v_mul_f32_e32 v15, 0x3fb8aa3b, v15
	v_exp_f32_e32 v140, v15
	v_sub_f32_e32 v15, v54, v41
	v_mul_f32_e32 v15, 0x3fb8aa3b, v15
	v_exp_f32_e32 v141, v15
	v_sub_f32_e32 v15, v56, v41
	v_mul_f32_e32 v15, 0x3fb8aa3b, v15
	v_exp_f32_e32 v58, v15
	v_sub_f32_e32 v15, v57, v41
	v_mul_f32_e32 v15, 0x3fb8aa3b, v15
	v_exp_f32_e32 v59, v15
	v_sub_f32_e32 v15, v55, v41
	v_sub_f32_e32 v10, v47, v41
	v_mul_f32_e32 v15, 0x3fb8aa3b, v15
	v_mul_f32_e32 v10, 0x3fb8aa3b, v10
	v_sub_f32_e32 v11, v48, v41
	v_exp_f32_e32 v60, v15
	v_sub_f32_e32 v15, v61, v41
	v_exp_f32_e32 v10, v10
	v_mul_f32_e32 v11, 0x3fb8aa3b, v11
	v_mul_f32_e32 v15, 0x3fb8aa3b, v15
	v_exp_f32_e32 v11, v11
	v_exp_f32_e32 v61, v15
	v_sub_f32_e32 v15, v62, v41
	v_mul_f32_e32 v15, 0x3fb8aa3b, v15
	v_exp_f32_e32 v62, v15
	v_sub_f32_e32 v15, v63, v41
	v_add_f32_e32 v12, 0, v10
	v_mul_f32_e32 v15, 0x3fb8aa3b, v15
	v_add_f32_e32 v13, v11, v12
	v_sub_f32_e32 v12, v49, v41
	v_exp_f32_e32 v63, v15
	v_sub_f32_e32 v15, v64, v41
	v_mul_f32_e32 v12, 0x3fb8aa3b, v12
	v_mul_f32_e32 v15, 0x3fb8aa3b, v15
	v_exp_f32_e32 v12, v12
	v_exp_f32_e32 v64, v15
	v_sub_f32_e32 v15, v65, v41
	v_mul_f32_e32 v15, 0x3fb8aa3b, v15
	v_exp_f32_e32 v65, v15
	v_sub_f32_e32 v15, v137, v41
	v_mul_f32_e32 v15, 0x3fb8aa3b, v15
	v_add_f32_e32 v14, v12, v13
	v_sub_f32_e32 v13, v50, v41
	v_exp_f32_e32 v50, v15
	v_sub_f32_e32 v15, v142, v41
	v_mul_f32_e32 v13, 0x3fb8aa3b, v13
	v_mul_f32_e32 v15, 0x3fb8aa3b, v15
	v_exp_f32_e32 v13, v13
	v_exp_f32_e32 v51, v15
	v_sub_f32_e32 v15, v143, v41
	v_mul_f32_e32 v15, 0x3fb8aa3b, v15
	v_exp_f32_e32 v52, v15
	v_sub_f32_e32 v15, v144, v41
	v_mul_f32_e32 v15, 0x3fb8aa3b, v15
	v_add_f32_e32 v14, v13, v14
	v_exp_f32_e32 v53, v15
	v_sub_f32_e32 v15, v145, v41
	v_add_f32_e32 v14, v138, v14
	v_mul_f32_e32 v15, 0x3fb8aa3b, v15
	v_add_f32_e32 v14, v139, v14
	v_exp_f32_e32 v54, v15
	v_sub_f32_e32 v15, v162, v41
	v_add_f32_e32 v14, v140, v14
	v_mul_f32_e32 v15, 0x3fb8aa3b, v15
	v_add_f32_e32 v14, v141, v14
	v_exp_f32_e32 v55, v15
	v_sub_f32_e32 v15, v163, v41
	v_add_f32_e32 v14, v58, v14
	v_mul_f32_e32 v15, 0x3fb8aa3b, v15
	v_add_f32_e32 v14, v59, v14
	v_exp_f32_e32 v56, v15
	v_sub_f32_e32 v15, v164, v41
	v_add_f32_e32 v14, v60, v14
	v_mul_f32_e32 v15, 0x3fb8aa3b, v15
	v_add_f32_e32 v14, v61, v14
	v_exp_f32_e32 v57, v15
	v_sub_f32_e32 v15, v165, v41
	v_add_f32_e32 v14, v62, v14
	v_mul_f32_e32 v15, 0x3fb8aa3b, v15
	v_add_f32_e32 v14, v63, v14
	v_exp_f32_e32 v42, v15
	v_sub_f32_e32 v15, v166, v41
	v_add_f32_e32 v14, v64, v14
	v_mul_f32_e32 v15, 0x3fb8aa3b, v15
	v_add_f32_e32 v14, v65, v14
	v_exp_f32_e32 v43, v15
	v_sub_f32_e32 v15, v167, v41
	v_add_f32_e32 v14, v50, v14
	v_mul_f32_e32 v15, 0x3fb8aa3b, v15
	v_add_f32_e32 v14, v51, v14
	v_exp_f32_e32 v44, v15
	v_sub_f32_e32 v15, v168, v41
	v_add_f32_e32 v14, v52, v14
	v_mul_f32_e32 v15, 0x3fb8aa3b, v15
	v_add_f32_e32 v14, v53, v14
	v_exp_f32_e32 v45, v15
	v_sub_f32_e32 v15, v169, v41
	v_add_f32_e32 v14, v54, v14
	v_mul_f32_e32 v15, 0x3fb8aa3b, v15
	v_add_f32_e32 v14, v55, v14
	v_exp_f32_e32 v46, v15
	v_sub_f32_e32 v15, v170, v41
	v_add_f32_e32 v14, v56, v14
	v_mul_f32_e32 v15, 0x3fb8aa3b, v15
	v_add_f32_e32 v14, v57, v14
	v_exp_f32_e32 v47, v15
	v_sub_f32_e32 v15, v171, v41
	v_add_f32_e32 v14, v42, v14
	v_mul_f32_e32 v15, 0x3fb8aa3b, v15
	v_add_f32_e32 v14, v43, v14
	v_exp_f32_e32 v48, v15
	v_sub_f32_e32 v15, v172, v41
	v_add_f32_e32 v14, v44, v14
	v_mul_f32_e32 v15, 0x3fb8aa3b, v15
	v_add_f32_e32 v14, v45, v14
	v_exp_f32_e32 v49, v15
	v_add_f32_e32 v14, v46, v14
	v_add_f32_e32 v14, v47, v14
	v_add_f32_e32 v14, v48, v14
	v_add_f32_e32 v15, v49, v14
	v_sub_f32_e32 v14, v173, v41
	v_mul_f32_e32 v14, 0x3fb8aa3b, v14
	v_exp_f32_e32 v14, v14
	v_sub_f32_e32 v36, v36, v41
	v_mul_f32_e32 v36, 0x3fb8aa3b, v36
	v_sub_f32_e32 v37, v37, v41
	v_add_f32_e32 v16, v14, v15
	v_sub_f32_e32 v15, v174, v41
	v_mul_f32_e32 v15, 0x3fb8aa3b, v15
	v_exp_f32_e32 v15, v15
	v_exp_f32_e32 v36, v36
	v_mul_f32_e32 v37, 0x3fb8aa3b, v37
	v_sub_f32_e32 v38, v38, v41
	v_add_f32_e32 v17, v15, v16
	v_sub_f32_e32 v16, v175, v41
	v_mul_f32_e32 v16, 0x3fb8aa3b, v16
	v_exp_f32_e32 v16, v16
	v_exp_f32_e32 v37, v37
	v_mul_f32_e32 v38, 0x3fb8aa3b, v38
	v_sub_f32_e32 v39, v39, v41
	v_add_f32_e32 v137, v16, v17
	v_sub_f32_e32 v17, v176, v41
	v_mul_f32_e32 v17, 0x3fb8aa3b, v17
	v_exp_f32_e32 v17, v17
	v_exp_f32_e32 v38, v38
	v_mul_f32_e32 v39, 0x3fb8aa3b, v39
	v_exp_f32_e32 v39, v39
	v_add_f32_e32 v137, v17, v137
	v_add_f32_e32 v137, v36, v137
	v_add_f32_e32 v137, v37, v137
	v_add_f32_e32 v137, v38, v137
	v_add_f32_e32 v137, v39, v137
	ds_swizzle_b32 v142, v137 offset:swizzle(SWAP,16)
	v_sub_f32_e32 v40, v40, v41
	v_mul_f32_e32 v40, 0x3fb8aa3b, v40
	v_exp_f32_e32 v40, v40
	s_waitcnt lgkmcnt(0)
	v_add_f32_e32 v137, v137, v142
	ds_bpermute_b32 v142, v19, v137
	s_waitcnt lgkmcnt(0)
	v_add_f32_e32 v137, v137, v142
	v_add_f32_e32 v40, v40, v137
	v_div_scale_f32 v41, s[2:3], v40, v40, 1.0
	v_rcp_f32_e32 v137, v41
	s_nop 0
	v_fma_f32 v142, -v41, v137, 1.0
	v_fmac_f32_e32 v137, v142, v137
	v_div_scale_f32 v142, vcc, 1.0, v40, 1.0
	v_mul_f32_e32 v143, v142, v137
	v_fma_f32 v144, -v41, v143, v142
	v_fmac_f32_e32 v143, v144, v137
	v_fma_f32 v41, -v41, v143, v142
	v_div_fmas_f32 v41, v41, v137, v143
	v_div_fixup_f32 v40, v41, v40, 1.0
	v_mul_f32_e32 v12, v40, v12
	v_mul_f32_e32 v13, v40, v13
	v_mul_f32_e32 v10, v40, v10
	v_mul_f32_e32 v11, v40, v11
	v_mul_f32_e32 v140, v40, v140
	v_mul_f32_e32 v141, v40, v141
	v_mul_f32_e32 v138, v40, v138
	v_mul_f32_e32 v139, v40, v139
	v_add_u32_e32 v137, 0x9000, v132
	v_cvt_pk_bf16_f32 v10, v10, v11
	v_cvt_pk_bf16_f32 v11, v12, v13
	v_cvt_pk_bf16_f32 v12, v138, v139
	v_cvt_pk_bf16_f32 v13, v140, v141
	ds_read2_b64 v[138:141], v137 offset1:4
	s_waitcnt lgkmcnt(0)
	v_mfma_f32_16x16x32_bf16 v[142:145], v[138:141], v[10:13], 0
	v_add_u32_e32 v138, 0xb000, v132
	v_add_u32_e32 v139, 0xd000, v132
	v_add_u32_e32 v140, 0xf000, v132
	ds_read2_b64 v[162:165], v138 offset0:32 offset1:36
	ds_read2_b64 v[166:169], v139 offset0:64 offset1:68
	ds_read2_b64 v[170:173], v140 offset0:96 offset1:100
	v_mul_f32_e32 v58, v40, v58
	v_mul_f32_e32 v59, v40, v59
	s_waitcnt lgkmcnt(2)
	v_mfma_f32_16x16x32_bf16 v[162:165], v[162:165], v[10:13], 0
	v_mul_f32_e64 v60, v60, v40
	v_mul_f32_e64 v61, v61, v40
	v_mul_f32_e32 v52, v40, v52
	v_mul_f32_e32 v53, v40, v53
	v_mul_f32_e32 v50, v40, v50
	v_mul_f32_e32 v51, v40, v51
	s_waitcnt lgkmcnt(1)
	v_mfma_f32_16x16x32_bf16 v[166:169], v[166:169], v[10:13], 0
	v_mul_f32_e64 v56, v56, v40
	v_mul_f32_e64 v57, v57, v40
	v_mul_f32_e32 v54, v40, v54
	v_mul_f32_e32 v55, v40, v55
	v_mul_f32_e32 v44, v40, v44
	v_mul_f32_e32 v45, v40, v45
	s_waitcnt lgkmcnt(0)
	v_mfma_f32_16x16x32_bf16 v[10:13], v[170:173], v[10:13], 0
	v_mul_f32_e64 v170, v64, v40
	v_mul_f32_e64 v171, v65, v40
	v_mul_f32_e32 v64, v40, v62
	v_mul_f32_e32 v65, v40, v63
	v_cvt_pk_bf16_f32 v62, v58, v59
	v_add_u32_e32 v58, 0x9000, v133
	v_cvt_pk_bf16_f32 v63, v60, v61
	v_cvt_pk_bf16_f32 v64, v64, v65
	v_cvt_pk_bf16_f32 v65, v170, v171
	ds_read2_b64 v[170:173], v58 offset1:4
	v_add_u32_e32 v59, 0xb000, v133
	s_waitcnt lgkmcnt(0)
	v_mfma_f32_16x16x32_bf16 v[142:145], v[170:173], v[62:65], v[142:145]
	ds_read2_b64 v[170:173], v59 offset0:32 offset1:36
	v_add_u32_e32 v60, 0xd000, v133
	v_add_u32_e32 v61, 0xf000, v133
	s_waitcnt lgkmcnt(0)
	v_mfma_f32_16x16x32_bf16 v[162:165], v[170:173], v[62:65], v[162:165]
	ds_read2_b64 v[170:173], v60 offset0:64 offset1:68
	v_mul_f32_e32 v42, v40, v42
	v_mul_f32_e32 v43, v40, v43
	v_mul_f32_e32 v48, v40, v48
	v_mul_f32_e32 v49, v40, v49
	s_waitcnt lgkmcnt(0)
	v_mfma_f32_16x16x32_bf16 v[166:169], v[170:173], v[62:65], v[166:169]
	ds_read2_b64 v[170:173], v61 offset0:96 offset1:100
	v_cvt_pk_bf16_f32 v50, v50, v51
	v_cvt_pk_bf16_f32 v51, v52, v53
	v_cvt_pk_bf16_f32 v52, v54, v55
	v_cvt_pk_bf16_f32 v53, v56, v57
	v_add_u32_e32 v56, 0x9000, v134
	s_waitcnt lgkmcnt(0)
	v_mfma_f32_16x16x32_bf16 v[10:13], v[170:173], v[62:65], v[10:13]
	ds_read2_b64 v[62:65], v56 offset1:4
	v_add_u32_e32 v57, 0xb000, v134
	v_mul_f32_e32 v46, v40, v46
	v_mul_f32_e32 v47, v40, v47
	s_waitcnt lgkmcnt(0)
	v_mfma_f32_16x16x32_bf16 v[142:145], v[62:65], v[50:53], v[142:145]
	ds_read2_b64 v[62:65], v57 offset0:32 offset1:36
	v_add_u32_e32 v141, 0xd000, v135
	v_mul_f32_e32 v16, v40, v16
	v_mul_f32_e32 v17, v40, v17
	s_waitcnt lgkmcnt(0)
	v_mfma_f32_16x16x32_bf16 v[162:165], v[62:65], v[50:53], v[162:165]
	v_add_u32_e32 v62, 0xd000, v134
	ds_read2_b64 v[170:173], v62 offset0:64 offset1:68
	v_add_u32_e32 v63, 0xf000, v134
	v_add_u32_e32 v64, 0x9000, v135
	s_waitcnt lgkmcnt(0)
	v_mfma_f32_16x16x32_bf16 v[166:169], v[170:173], v[50:53], v[166:169]
	ds_read2_b64 v[170:173], v63 offset0:96 offset1:100
	v_cvt_pk_bf16_f32 v42, v42, v43
	v_cvt_pk_bf16_f32 v43, v44, v45
	v_cvt_pk_bf16_f32 v44, v46, v47
	v_cvt_pk_bf16_f32 v45, v48, v49
	ds_read2_b64 v[46:49], v64 offset1:4
	v_add_u32_e32 v65, 0xb000, v135
	s_waitcnt lgkmcnt(1)
	v_mfma_f32_16x16x32_bf16 v[10:13], v[170:173], v[50:53], v[10:13]
	ds_read2_b64 v[50:53], v65 offset0:32 offset1:36
	v_mul_f32_e32 v14, v40, v14
	v_mul_f32_e32 v15, v40, v15
	v_mul_f32_e32 v38, v40, v38
	v_mul_f32_e32 v39, v40, v39
	s_waitcnt lgkmcnt(1)
	v_mfma_f32_16x16x32_bf16 v[46:49], v[46:49], v[42:45], v[142:145]
	v_mul_f32_e64 v36, v36, v40
	v_mul_f32_e64 v37, v37, v40
	s_nop 0
	ds_read2_b64 v[142:145], v141 offset0:64 offset1:68
	s_waitcnt lgkmcnt(1)
	v_mfma_f32_16x16x32_bf16 v[50:53], v[50:53], v[42:45], v[162:165]
	s_waitcnt lgkmcnt(0)
	v_mfma_f32_16x16x32_bf16 v[162:165], v[142:145], v[42:45], v[166:169]
	v_add_u32_e32 v142, 0xf000, v135
	v_add_u32_e32 v143, 0x9000, v136
	s_nop 0
	ds_read2_b64 v[166:169], v142 offset0:96 offset1:100
	v_cvt_pk_bf16_f32 v14, v14, v15
	v_cvt_pk_bf16_f32 v15, v16, v17
	v_cvt_pk_bf16_f32 v16, v36, v37
	v_cvt_pk_bf16_f32 v17, v38, v39
	ds_read2_b64 v[36:39], v143 offset1:4
	v_add_u32_e32 v145, 0xd000, v136
	s_waitcnt lgkmcnt(1)
	v_mfma_f32_16x16x32_bf16 v[10:13], v[166:169], v[42:45], v[10:13]
	v_add_u32_e32 v144, 0xb000, v136
	ds_read2_b64 v[40:43], v144 offset0:32 offset1:36
	s_waitcnt lgkmcnt(1)
	v_mfma_f32_16x16x32_bf16 v[36:39], v[36:39], v[14:17], v[46:49]
	s_nop 2
	ds_read2_b64 v[44:47], v145 offset0:64 offset1:68
	s_waitcnt lgkmcnt(0)
	v_mfma_f32_16x16x32_bf16 v[44:47], v[44:47], v[14:17], v[162:165]
	s_nop 2
	v_add_u32_e32 v162, 0xf000, v136
	v_mfma_f32_16x16x32_bf16 v[40:43], v[40:43], v[14:17], v[50:53]
	s_nop 2
	ds_read2_b64 v[48:51], v162 offset0:96 offset1:100
	s_waitcnt lgkmcnt(0)
	v_mfma_f32_16x16x32_bf16 v[10:13], v[48:51], v[14:17], v[10:13]
	v_cvt_pk_bf16_f32 v14, v36, v37
	v_cvt_pk_bf16_f32 v15, v38, v39
	global_store_dwordx2 v[34:35], v[14:15], off offset:-64
	v_cvt_pk_bf16_f32 v14, v40, v41
	v_cvt_pk_bf16_f32 v15, v42, v43
	global_store_dwordx2 v[34:35], v[14:15], off offset:-32
	v_cvt_pk_bf16_f32 v14, v44, v45
	v_cvt_pk_bf16_f32 v15, v46, v47
	global_store_dwordx2 v[34:35], v[14:15], off
	v_cvt_pk_bf16_f32 v10, v10, v11
	v_cvt_pk_bf16_f32 v11, v12, v13
	s_nop 4
	global_store_dwordx2 v[34:35], v[10:11], off offset:32
	v_mov_b64_e32 v[12:13], v[8:9]
	v_lshl_add_u64 v[34:35], v[34:35], 0, s[94:95]
	v_mov_b64_e32 v[10:11], v[6:7]
	s_cbranch_scc0 .LBB0_124
	v_add_u32_e32 v79, 0, v235
	v_add_u32_e32 v80, 1, v235
	v_add_u32_e32 v81, 2, v235
	v_add_u32_e32 v82, 3, v235
	v_add_u32_e32 v84, 16, v235
	v_add_u32_e32 v85, 17, v235
	v_add_u32_e32 v86, 18, v235
	v_add_u32_e32 v87, 19, v235
	v_add_u32_e32 v89, 32, v235
	v_add_u32_e32 v90, 33, v235
	v_add_u32_e32 v91, 34, v235
	v_add_u32_e32 v92, 35, v235
	v_add_u32_e32 v94, 48, v235
	v_add_u32_e32 v95, 49, v235
	v_add_u32_e32 v96, 50, v235
	v_add_u32_e32 v97, 51, v235
	v_add_u32_e32 v99, 64, v235
	v_add_u32_e32 v100, 65, v235
	v_add_u32_e32 v101, 66, v235
	v_add_u32_e32 v102, 67, v235
	v_add_u32_e32 v104, 80, v235
	v_add_u32_e32 v105, 81, v235
	v_add_u32_e32 v106, 82, v235
	v_add_u32_e32 v107, 83, v235
	v_add_u32_e32 v109, 96, v235
	v_add_u32_e32 v110, 97, v235
	v_add_u32_e32 v111, 98, v235
	v_add_u32_e32 v112, 99, v235
	v_add_u32_e32 v114, 112, v235
	v_add_u32_e32 v115, 113, v235
	v_add_u32_e32 v116, 114, v235
	v_add_u32_e32 v117, 115, v235
	v_add_u32_e32 v119, 128, v235
	v_add_u32_e32 v120, 129, v235
	v_add_u32_e32 v121, 130, v235
	v_add_u32_e32 v122, 131, v235
	v_add_u32_e32 v124, 144, v235
	v_add_u32_e32 v125, 145, v235
	v_add_u32_e32 v126, 146, v235
	v_add_u32_e32 v127, 147, v235
	s_lshl_b32 s2, s23, 3
	s_add_i32 s2, s2, s19
	s_mov_b32 s3, s89
	s_lshl_b64 s[2:3], s[2:3], 2
	v_mov_b32_e32 v12, v22
	s_add_u32 s2, s48, s2
	s_addc_u32 s3, s49, s3
	v_lshl_add_u64 v[10:11], v[30:31], 1, v[24:25]
	v_cndmask_b32_e64 v16, v195, v12, s[38:39]
	global_load_dword v163, v1, s[2:3] offset:28
	v_add_u32_e32 v17, 0x80, v12
	ds_read_b128 v[12:15], v78
	ds_read_b128 v[30:33], v78 offset:64
	s_waitcnt lgkmcnt(1)
	v_mfma_f32_16x16x32_bf16 v[12:15], v[12:15], v[2:5], 0
	v_sub_u32_e32 v55, v17, v109
	s_or_b32 s88, s88, 0x380
	s_add_i32 s22, s22, s92
	s_waitcnt lgkmcnt(0)
	v_mfma_f32_16x16x32_bf16 v[12:15], v[30:33], v[6:9], v[12:15]
	v_sub_u32_e32 v30, v17, v79
	v_sub_u32_e32 v31, v16, v30
	v_or_b32_e32 v31, v31, v30
	v_and_b32_e32 v30, 0x7f, v30
	v_lshl_add_u32 v30, v30, 2, s97
	ds_read_b32 v30, v30
	v_ashrrev_i32_e32 v31, 31, v31
	v_and_b32_e32 v31, 0xff800000, v31
	s_xor_b64 s[42:43], s[42:43], s[44:45]
	s_cmpk_gt_i32 s22, 0xff
	s_waitcnt lgkmcnt(0)
	v_add_f32_e32 v12, v12, v30
	v_sub_u32_e32 v30, v17, v80
	v_add_f32_e32 v12, v12, v31
	v_sub_u32_e32 v31, v16, v30
	v_or_b32_e32 v31, v31, v30
	v_and_b32_e32 v30, 0x7f, v30
	v_lshl_add_u32 v30, v30, 2, s97
	ds_read_b32 v30, v30
	v_ashrrev_i32_e32 v31, 31, v31
	v_and_b32_e32 v31, 0xff800000, v31
	s_waitcnt lgkmcnt(0)
	v_add_f32_e32 v13, v13, v30
	v_add_f32_e32 v13, v13, v31
	v_sub_u32_e32 v31, v17, v81
	v_sub_u32_e32 v32, v16, v31
	v_or_b32_e32 v32, v32, v31
	v_and_b32_e32 v31, 0x7f, v31
	v_lshl_add_u32 v31, v31, 2, s97
	ds_read_b32 v31, v31
	v_ashrrev_i32_e32 v32, 31, v32
	v_and_b32_e32 v32, 0xff800000, v32
	v_max3_f32 v30, v12, s96, v13
	s_waitcnt lgkmcnt(0)
	v_add_f32_e32 v14, v14, v31
	v_sub_u32_e32 v31, v17, v82
	v_add_f32_e32 v14, v14, v32
	v_sub_u32_e32 v32, v16, v31
	v_or_b32_e32 v32, v32, v31
	v_and_b32_e32 v31, 0x7f, v31
	v_lshl_add_u32 v31, v31, 2, s97
	ds_read_b32 v31, v31
	v_ashrrev_i32_e32 v32, 31, v32
	v_and_b32_e32 v32, 0xff800000, v32
	s_waitcnt lgkmcnt(0)
	v_add_f32_e32 v15, v15, v31
	v_add_f32_e32 v15, v15, v32
	v_max3_f32 v38, v30, v14, v15
	ds_read_b128 v[30:33], v83
	ds_read_b128 v[34:37], v83 offset:64
	s_waitcnt lgkmcnt(1)
	v_mfma_f32_16x16x32_bf16 v[30:33], v[30:33], v[2:5], 0
	s_waitcnt lgkmcnt(0)
	v_mfma_f32_16x16x32_bf16 v[30:33], v[34:37], v[6:9], v[30:33]
	v_sub_u32_e32 v34, v17, v84
	v_sub_u32_e32 v35, v16, v34
	v_or_b32_e32 v35, v35, v34
	v_and_b32_e32 v34, 0x7f, v34
	v_lshl_add_u32 v34, v34, 2, s97
	ds_read_b32 v34, v34
	v_ashrrev_i32_e32 v35, 31, v35
	v_and_b32_e32 v35, 0xff800000, v35
	s_waitcnt lgkmcnt(0)
	v_add_f32_e32 v30, v30, v34
	v_sub_u32_e32 v34, v17, v85
	v_add_f32_e32 v30, v30, v35
	v_sub_u32_e32 v35, v16, v34
	v_or_b32_e32 v35, v35, v34
	v_and_b32_e32 v34, 0x7f, v34
	v_lshl_add_u32 v34, v34, 2, s97
	ds_read_b32 v34, v34
	v_ashrrev_i32_e32 v35, 31, v35
	v_and_b32_e32 v35, 0xff800000, v35
	s_waitcnt lgkmcnt(0)
	v_add_f32_e32 v31, v31, v34
	v_add_f32_e32 v31, v31, v35
	v_sub_u32_e32 v35, v17, v86
	v_sub_u32_e32 v36, v16, v35
	v_or_b32_e32 v36, v36, v35
	v_and_b32_e32 v35, 0x7f, v35
	v_lshl_add_u32 v35, v35, 2, s97
	ds_read_b32 v35, v35
	v_ashrrev_i32_e32 v36, 31, v36
	v_and_b32_e32 v36, 0xff800000, v36
	v_max3_f32 v34, v38, v30, v31
	s_waitcnt lgkmcnt(0)
	v_add_f32_e32 v32, v32, v35
	v_sub_u32_e32 v35, v17, v87
	v_add_f32_e32 v32, v32, v36
	v_sub_u32_e32 v36, v16, v35
	v_or_b32_e32 v36, v36, v35
	v_and_b32_e32 v35, 0x7f, v35
	v_lshl_add_u32 v35, v35, 2, s97
	ds_read_b32 v35, v35
	v_ashrrev_i32_e32 v36, 31, v36
	v_and_b32_e32 v36, 0xff800000, v36
	s_waitcnt lgkmcnt(0)
	v_add_f32_e32 v33, v33, v35
	v_add_f32_e32 v33, v33, v36
	v_max3_f32 v42, v34, v32, v33
	ds_read_b128 v[34:37], v88
	ds_read_b128 v[38:41], v88 offset:64
	s_waitcnt lgkmcnt(1)
	v_mfma_f32_16x16x32_bf16 v[34:37], v[34:37], v[2:5], 0
	s_waitcnt lgkmcnt(0)
	v_mfma_f32_16x16x32_bf16 v[34:37], v[38:41], v[6:9], v[34:37]
	v_sub_u32_e32 v38, v17, v89
	v_sub_u32_e32 v39, v16, v38
	v_or_b32_e32 v39, v39, v38
	v_and_b32_e32 v38, 0x7f, v38
	v_lshl_add_u32 v38, v38, 2, s97
	ds_read_b32 v38, v38
	v_ashrrev_i32_e32 v39, 31, v39
	v_and_b32_e32 v39, 0xff800000, v39
	s_waitcnt lgkmcnt(0)
	v_add_f32_e32 v34, v34, v38
	v_sub_u32_e32 v38, v17, v90
	v_add_f32_e32 v34, v34, v39
	v_sub_u32_e32 v39, v16, v38
	v_or_b32_e32 v39, v39, v38
	v_and_b32_e32 v38, 0x7f, v38
	v_lshl_add_u32 v38, v38, 2, s97
	ds_read_b32 v38, v38
	v_ashrrev_i32_e32 v39, 31, v39
	v_and_b32_e32 v39, 0xff800000, v39
	s_waitcnt lgkmcnt(0)
	v_add_f32_e32 v35, v35, v38
	v_add_f32_e32 v35, v35, v39
	v_sub_u32_e32 v39, v17, v91
	v_sub_u32_e32 v40, v16, v39
	v_or_b32_e32 v40, v40, v39
	v_and_b32_e32 v39, 0x7f, v39
	v_lshl_add_u32 v39, v39, 2, s97
	ds_read_b32 v39, v39
	v_ashrrev_i32_e32 v40, 31, v40
	v_and_b32_e32 v40, 0xff800000, v40
	v_max3_f32 v38, v42, v34, v35
	s_waitcnt lgkmcnt(0)
	v_add_f32_e32 v36, v36, v39
	v_sub_u32_e32 v39, v17, v92
	v_add_f32_e32 v36, v36, v40
	v_sub_u32_e32 v40, v16, v39
	v_or_b32_e32 v40, v40, v39
	v_and_b32_e32 v39, 0x7f, v39
	v_lshl_add_u32 v39, v39, 2, s97
	ds_read_b32 v39, v39
	v_ashrrev_i32_e32 v40, 31, v40
	v_and_b32_e32 v40, 0xff800000, v40
	s_waitcnt lgkmcnt(0)
	v_add_f32_e32 v37, v37, v39
	v_add_f32_e32 v37, v37, v40
	v_max3_f32 v46, v38, v36, v37
	ds_read_b128 v[38:41], v93
	ds_read_b128 v[42:45], v93 offset:64
	s_waitcnt lgkmcnt(1)
	v_mfma_f32_16x16x32_bf16 v[38:41], v[38:41], v[2:5], 0
	s_waitcnt lgkmcnt(0)
	v_mfma_f32_16x16x32_bf16 v[38:41], v[42:45], v[6:9], v[38:41]
	v_sub_u32_e32 v42, v17, v94
	v_sub_u32_e32 v43, v16, v42
	v_or_b32_e32 v43, v43, v42
	v_and_b32_e32 v42, 0x7f, v42
	v_lshl_add_u32 v42, v42, 2, s97
	ds_read_b32 v42, v42
	v_ashrrev_i32_e32 v43, 31, v43
	v_and_b32_e32 v43, 0xff800000, v43
	s_waitcnt lgkmcnt(0)
	v_add_f32_e32 v38, v38, v42
	v_sub_u32_e32 v42, v17, v95
	v_add_f32_e32 v38, v38, v43
	v_sub_u32_e32 v43, v16, v42
	v_or_b32_e32 v43, v43, v42
	v_and_b32_e32 v42, 0x7f, v42
	v_lshl_add_u32 v42, v42, 2, s97
	ds_read_b32 v42, v42
	v_ashrrev_i32_e32 v43, 31, v43
	v_and_b32_e32 v43, 0xff800000, v43
	s_waitcnt lgkmcnt(0)
	v_add_f32_e32 v39, v39, v42
	v_add_f32_e32 v39, v39, v43
	v_sub_u32_e32 v43, v17, v96
	v_sub_u32_e32 v44, v16, v43
	v_or_b32_e32 v44, v44, v43
	v_and_b32_e32 v43, 0x7f, v43
	v_lshl_add_u32 v43, v43, 2, s97
	ds_read_b32 v43, v43
	v_ashrrev_i32_e32 v44, 31, v44
	v_and_b32_e32 v44, 0xff800000, v44
	v_max3_f32 v42, v46, v38, v39
	s_waitcnt lgkmcnt(0)
	v_add_f32_e32 v40, v40, v43
	v_sub_u32_e32 v43, v17, v97
	v_add_f32_e32 v40, v40, v44
	v_sub_u32_e32 v44, v16, v43
	v_or_b32_e32 v44, v44, v43
	v_and_b32_e32 v43, 0x7f, v43
	v_lshl_add_u32 v43, v43, 2, s97
	ds_read_b32 v43, v43
	v_ashrrev_i32_e32 v44, 31, v44
	v_and_b32_e32 v44, 0xff800000, v44
	s_waitcnt lgkmcnt(0)
	v_add_f32_e32 v41, v41, v43
	v_add_f32_e32 v41, v41, v44
	v_max3_f32 v50, v42, v40, v41
	ds_read_b128 v[42:45], v98
	ds_read_b128 v[46:49], v98 offset:64
	s_waitcnt lgkmcnt(1)
	v_mfma_f32_16x16x32_bf16 v[42:45], v[42:45], v[2:5], 0
	s_waitcnt lgkmcnt(0)
	v_mfma_f32_16x16x32_bf16 v[42:45], v[46:49], v[6:9], v[42:45]
	v_sub_u32_e32 v46, v17, v99
	v_sub_u32_e32 v47, v16, v46
	v_or_b32_e32 v47, v47, v46
	v_and_b32_e32 v46, 0x7f, v46
	v_lshl_add_u32 v46, v46, 2, s97
	ds_read_b32 v46, v46
	v_ashrrev_i32_e32 v47, 31, v47
	v_and_b32_e32 v47, 0xff800000, v47
	s_waitcnt lgkmcnt(0)
	v_add_f32_e32 v42, v42, v46
	v_sub_u32_e32 v46, v17, v100
	v_add_f32_e32 v42, v42, v47
	v_sub_u32_e32 v47, v16, v46
	v_or_b32_e32 v47, v47, v46
	v_and_b32_e32 v46, 0x7f, v46
	v_lshl_add_u32 v46, v46, 2, s97
	ds_read_b32 v46, v46
	v_ashrrev_i32_e32 v47, 31, v47
	v_and_b32_e32 v47, 0xff800000, v47
	s_waitcnt lgkmcnt(0)
	v_add_f32_e32 v43, v43, v46
	v_add_f32_e32 v43, v43, v47
	v_sub_u32_e32 v47, v17, v101
	v_sub_u32_e32 v48, v16, v47
	v_or_b32_e32 v48, v48, v47
	v_and_b32_e32 v47, 0x7f, v47
	v_lshl_add_u32 v47, v47, 2, s97
	ds_read_b32 v47, v47
	v_ashrrev_i32_e32 v48, 31, v48
	v_and_b32_e32 v48, 0xff800000, v48
	v_max3_f32 v46, v50, v42, v43
	s_waitcnt lgkmcnt(0)
	v_add_f32_e32 v44, v44, v47
	v_sub_u32_e32 v47, v17, v102
	v_add_f32_e32 v44, v44, v48
	v_sub_u32_e32 v48, v16, v47
	v_or_b32_e32 v48, v48, v47
	v_and_b32_e32 v47, 0x7f, v47
	v_lshl_add_u32 v47, v47, 2, s97
	ds_read_b32 v47, v47
	v_ashrrev_i32_e32 v48, 31, v48
	v_and_b32_e32 v48, 0xff800000, v48
	s_waitcnt lgkmcnt(0)
	v_add_f32_e32 v45, v45, v47
	v_add_f32_e32 v45, v45, v48
	v_max3_f32 v54, v46, v44, v45
	ds_read_b128 v[46:49], v103
	ds_read_b128 v[50:53], v103 offset:64
	s_waitcnt lgkmcnt(1)
	v_mfma_f32_16x16x32_bf16 v[46:49], v[46:49], v[2:5], 0
	s_waitcnt lgkmcnt(0)
	v_mfma_f32_16x16x32_bf16 v[46:49], v[50:53], v[6:9], v[46:49]
	v_sub_u32_e32 v50, v17, v104
	v_sub_u32_e32 v51, v16, v50
	v_or_b32_e32 v51, v51, v50
	v_and_b32_e32 v50, 0x7f, v50
	v_lshl_add_u32 v50, v50, 2, s97
	ds_read_b32 v50, v50
	v_ashrrev_i32_e32 v51, 31, v51
	v_and_b32_e32 v51, 0xff800000, v51
	s_waitcnt lgkmcnt(0)
	v_add_f32_e32 v46, v46, v50
	v_sub_u32_e32 v50, v17, v105
	v_add_f32_e32 v46, v46, v51
	v_sub_u32_e32 v51, v16, v50
	v_or_b32_e32 v51, v51, v50
	v_and_b32_e32 v50, 0x7f, v50
	v_lshl_add_u32 v50, v50, 2, s97
	ds_read_b32 v50, v50
	v_ashrrev_i32_e32 v51, 31, v51
	v_and_b32_e32 v51, 0xff800000, v51
	s_waitcnt lgkmcnt(0)
	v_add_f32_e32 v47, v47, v50
	v_add_f32_e32 v47, v47, v51
	v_sub_u32_e32 v51, v17, v106
	v_sub_u32_e32 v52, v16, v51
	v_or_b32_e32 v52, v52, v51
	v_and_b32_e32 v51, 0x7f, v51
	v_lshl_add_u32 v51, v51, 2, s97
	ds_read_b32 v51, v51
	v_ashrrev_i32_e32 v52, 31, v52
	v_and_b32_e32 v52, 0xff800000, v52
	v_max3_f32 v50, v54, v46, v47
	s_waitcnt lgkmcnt(0)
	v_add_f32_e32 v48, v48, v51
	v_sub_u32_e32 v51, v17, v107
	v_add_f32_e32 v48, v48, v52
	v_sub_u32_e32 v52, v16, v51
	v_or_b32_e32 v52, v52, v51
	v_and_b32_e32 v51, 0x7f, v51
	v_lshl_add_u32 v51, v51, 2, s97
	ds_read_b32 v51, v51
	v_ashrrev_i32_e32 v52, 31, v52
	v_and_b32_e32 v52, 0xff800000, v52
	s_waitcnt lgkmcnt(0)
	v_add_f32_e32 v49, v49, v51
	v_add_f32_e32 v49, v49, v52
	v_max3_f32 v54, v50, v48, v49
	ds_read_b128 v[50:53], v108
	ds_read_b128 v[164:167], v108 offset:64
	s_waitcnt lgkmcnt(1)
	v_mfma_f32_16x16x32_bf16 v[50:53], v[50:53], v[2:5], 0
	s_waitcnt lgkmcnt(0)
	v_mfma_f32_16x16x32_bf16 v[50:53], v[164:167], v[6:9], v[50:53]
	v_sub_u32_e32 v164, v16, v55
	v_or_b32_e32 v164, v164, v55
	v_and_b32_e32 v55, 0x7f, v55
	v_lshl_add_u32 v55, v55, 2, s97
	ds_read_b32 v55, v55
	v_ashrrev_i32_e32 v164, 31, v164
	v_and_b32_e32 v164, 0xff800000, v164
	s_waitcnt lgkmcnt(0)
	v_add_f32_e32 v50, v50, v55
	v_sub_u32_e32 v55, v17, v110
	v_add_f32_e32 v50, v50, v164
	v_sub_u32_e32 v164, v16, v55
	v_or_b32_e32 v164, v164, v55
	v_and_b32_e32 v55, 0x7f, v55
	v_lshl_add_u32 v55, v55, 2, s97
	ds_read_b32 v55, v55
	v_ashrrev_i32_e32 v164, 31, v164
	v_and_b32_e32 v164, 0xff800000, v164
	s_waitcnt lgkmcnt(0)
	v_add_f32_e32 v51, v51, v55
	v_sub_u32_e32 v55, v17, v111
	v_add_f32_e32 v51, v51, v164
	v_sub_u32_e32 v164, v16, v55
	v_or_b32_e32 v164, v164, v55
	v_and_b32_e32 v55, 0x7f, v55
	v_lshl_add_u32 v55, v55, 2, s97
	ds_read_b32 v55, v55
	v_ashrrev_i32_e32 v164, 31, v164
	v_and_b32_e32 v164, 0xff800000, v164
	v_max3_f32 v54, v54, v50, v51
	s_waitcnt lgkmcnt(0)
	v_add_f32_e32 v52, v52, v55
	v_sub_u32_e32 v55, v17, v112
	v_add_f32_e32 v52, v52, v164
	v_sub_u32_e32 v164, v16, v55
	v_or_b32_e32 v164, v164, v55
	v_and_b32_e32 v55, 0x7f, v55
	v_lshl_add_u32 v55, v55, 2, s97
	ds_read_b32 v55, v55
	v_ashrrev_i32_e32 v164, 31, v164
	v_and_b32_e32 v164, 0xff800000, v164
	s_waitcnt lgkmcnt(0)
	v_add_f32_e32 v53, v53, v55
	v_add_f32_e32 v53, v53, v164
	ds_read_b128 v[164:167], v113
	ds_read_b128 v[168:171], v113 offset:64
	v_max3_f32 v172, v54, v52, v53
	v_sub_u32_e32 v54, v17, v114
	s_waitcnt lgkmcnt(1)
	v_mfma_f32_16x16x32_bf16 v[164:167], v[164:167], v[2:5], 0
	v_sub_u32_e32 v55, v16, v54
	v_or_b32_e32 v55, v55, v54
	v_and_b32_e32 v54, 0x7f, v54
	v_lshl_add_u32 v54, v54, 2, s97
	ds_read_b32 v54, v54
	s_waitcnt lgkmcnt(1)
	v_mfma_f32_16x16x32_bf16 v[164:167], v[168:171], v[6:9], v[164:167]
	v_ashrrev_i32_e32 v55, 31, v55
	v_and_b32_e32 v55, 0xff800000, v55
	s_waitcnt lgkmcnt(0)
	s_nop 4
	v_add_f32_e32 v54, v164, v54
	v_add_f32_e32 v54, v54, v55
	v_sub_u32_e32 v55, v17, v115
	v_sub_u32_e32 v164, v16, v55
	v_or_b32_e32 v164, v164, v55
	v_and_b32_e32 v55, 0x7f, v55
	v_lshl_add_u32 v55, v55, 2, s97
	ds_read_b32 v55, v55
	v_ashrrev_i32_e32 v164, 31, v164
	v_and_b32_e32 v164, 0xff800000, v164
	s_waitcnt lgkmcnt(0)
	v_add_f32_e32 v55, v165, v55
	v_add_f32_e32 v55, v55, v164
	v_sub_u32_e32 v164, v17, v116
	v_sub_u32_e32 v165, v16, v164
	v_or_b32_e32 v165, v165, v164
	v_and_b32_e32 v164, 0x7f, v164
	v_lshl_add_u32 v164, v164, 2, s97
	ds_read_b32 v164, v164
	v_ashrrev_i32_e32 v165, 31, v165
	v_and_b32_e32 v165, 0xff800000, v165
	v_max3_f32 v168, v172, v54, v55
	s_waitcnt lgkmcnt(0)
	v_add_f32_e32 v164, v166, v164
	v_add_f32_e32 v164, v164, v165
	v_sub_u32_e32 v165, v17, v117
	v_sub_u32_e32 v166, v16, v165
	v_or_b32_e32 v166, v166, v165
	v_and_b32_e32 v165, 0x7f, v165
	v_lshl_add_u32 v165, v165, 2, s97
	ds_read_b32 v165, v165
	v_ashrrev_i32_e32 v166, 31, v166
	v_and_b32_e32 v166, 0xff800000, v166
	s_waitcnt lgkmcnt(0)
	v_add_f32_e32 v165, v167, v165
	v_add_f32_e32 v165, v165, v166
	v_max3_f32 v174, v168, v164, v165
	ds_read_b128 v[166:169], v118
	ds_read_b128 v[170:173], v118 offset:64
	s_waitcnt lgkmcnt(1)
	v_mfma_f32_16x16x32_bf16 v[166:169], v[166:169], v[2:5], 0
	s_waitcnt lgkmcnt(0)
	v_mfma_f32_16x16x32_bf16 v[166:169], v[170:173], v[6:9], v[166:169]
	v_sub_u32_e32 v170, v17, v119
	v_sub_u32_e32 v171, v16, v170
	v_or_b32_e32 v171, v171, v170
	v_and_b32_e32 v170, 0x7f, v170
	v_lshl_add_u32 v170, v170, 2, s97
	ds_read_b32 v170, v170
	v_ashrrev_i32_e32 v171, 31, v171
	v_and_b32_e32 v171, 0xff800000, v171
	s_waitcnt lgkmcnt(0)
	v_add_f32_e32 v166, v166, v170
	v_sub_u32_e32 v170, v17, v120
	v_add_f32_e32 v166, v166, v171
	v_sub_u32_e32 v171, v16, v170
	v_or_b32_e32 v171, v171, v170
	v_and_b32_e32 v170, 0x7f, v170
	v_lshl_add_u32 v170, v170, 2, s97
	ds_read_b32 v170, v170
	v_ashrrev_i32_e32 v171, 31, v171
	v_and_b32_e32 v171, 0xff800000, v171
	s_waitcnt lgkmcnt(0)
	v_add_f32_e32 v167, v167, v170
	v_add_f32_e32 v167, v167, v171
	v_sub_u32_e32 v171, v17, v121
	v_sub_u32_e32 v172, v16, v171
	v_or_b32_e32 v172, v172, v171
	v_and_b32_e32 v171, 0x7f, v171
	v_lshl_add_u32 v171, v171, 2, s97
	ds_read_b32 v171, v171
	v_ashrrev_i32_e32 v172, 31, v172
	v_and_b32_e32 v172, 0xff800000, v172
	v_max3_f32 v170, v174, v166, v167
	s_waitcnt lgkmcnt(0)
	v_add_f32_e32 v168, v168, v171
	v_sub_u32_e32 v171, v17, v122
	v_add_f32_e32 v168, v168, v172
	v_sub_u32_e32 v172, v16, v171
	v_or_b32_e32 v172, v172, v171
	v_and_b32_e32 v171, 0x7f, v171
	v_lshl_add_u32 v171, v171, 2, s97
	ds_read_b32 v171, v171
	v_ashrrev_i32_e32 v172, 31, v172
	v_and_b32_e32 v172, 0xff800000, v172
	s_waitcnt lgkmcnt(0)
	v_add_f32_e32 v169, v169, v171
	v_add_f32_e32 v169, v169, v172
	v_max3_f32 v178, v170, v168, v169
	ds_read_b128 v[170:173], v123
	ds_read_b128 v[174:177], v123 offset:64
	s_waitcnt lgkmcnt(1)
	v_mfma_f32_16x16x32_bf16 v[2:5], v[170:173], v[2:5], 0
	s_waitcnt lgkmcnt(0)
	v_mfma_f32_16x16x32_bf16 v[2:5], v[174:177], v[6:9], v[2:5]
	v_sub_u32_e32 v6, v17, v124
	v_sub_u32_e32 v7, v16, v6
	v_or_b32_e32 v7, v7, v6
	v_and_b32_e32 v6, 0x7f, v6
	v_lshl_add_u32 v6, v6, 2, s97
	ds_read_b32 v6, v6
	v_ashrrev_i32_e32 v7, 31, v7
	v_and_b32_e32 v7, 0xff800000, v7
	s_waitcnt lgkmcnt(0)
	v_add_f32_e32 v2, v2, v6
	v_add_f32_e32 v170, v2, v7
	v_sub_u32_e32 v2, v17, v125
	v_sub_u32_e32 v6, v16, v2
	v_or_b32_e32 v6, v6, v2
	v_and_b32_e32 v2, 0x7f, v2
	v_lshl_add_u32 v2, v2, 2, s97
	ds_read_b32 v2, v2
	v_ashrrev_i32_e32 v6, 31, v6
	v_and_b32_e32 v6, 0xff800000, v6
	s_waitcnt lgkmcnt(0)
	v_add_f32_e32 v2, v3, v2
	v_sub_u32_e32 v3, v17, v126
	v_add_f32_e32 v171, v2, v6
	v_sub_u32_e32 v6, v16, v3
	v_or_b32_e32 v6, v6, v3
	v_and_b32_e32 v3, 0x7f, v3
	v_lshl_add_u32 v3, v3, 2, s97
	ds_read_b32 v3, v3
	v_ashrrev_i32_e32 v6, 31, v6
	v_and_b32_e32 v6, 0xff800000, v6
	v_max3_f32 v2, v178, v170, v171
	s_waitcnt lgkmcnt(0)
	v_add_f32_e32 v3, v4, v3
	v_add_f32_e32 v172, v3, v6
	v_sub_u32_e32 v3, v17, v127
	v_sub_u32_e32 v4, v16, v3
	v_or_b32_e32 v4, v4, v3
	v_and_b32_e32 v3, 0x7f, v3
	v_lshl_add_u32 v3, v3, 2, s97
	ds_read_b32 v3, v3
	v_ashrrev_i32_e32 v4, 31, v4
	v_and_b32_e32 v4, 0xff800000, v4
	s_waitcnt lgkmcnt(0)
	v_add_f32_e32 v3, v5, v3
	v_add_f32_e32 v173, v3, v4
	v_max3_f32 v2, v2, v172, v173
	ds_swizzle_b32 v3, v2 offset:swizzle(SWAP,16)
	s_waitcnt lgkmcnt(0)
	v_max_f32_e32 v3, v3, v3
	v_max_f32_e32 v2, v2, v3
	ds_bpermute_b32 v3, v19, v2
	s_waitcnt vmcnt(0) lgkmcnt(0)
	v_max3_f32 v174, v2, v3, v163
	v_sub_f32_e32 v2, v12, v174
	v_mul_f32_e32 v2, 0x3fb8aa3b, v2
	v_sub_f32_e32 v3, v13, v174
	v_exp_f32_e32 v2, v2
	v_mul_f32_e32 v3, 0x3fb8aa3b, v3
	v_exp_f32_e32 v3, v3
	v_sub_f32_e32 v7, v30, v174
	v_add_f32_e32 v4, 0, v2
	v_mul_f32_e32 v7, 0x3fb8aa3b, v7
	v_add_f32_e32 v5, v3, v4
	v_sub_f32_e32 v4, v14, v174
	v_mul_f32_e32 v4, 0x3fb8aa3b, v4
	v_exp_f32_e32 v4, v4
	v_exp_f32_e32 v8, v7
	v_sub_f32_e32 v7, v31, v174
	v_mul_f32_e32 v7, 0x3fb8aa3b, v7
	v_add_f32_e32 v6, v4, v5
	v_sub_f32_e32 v5, v15, v174
	v_mul_f32_e32 v5, 0x3fb8aa3b, v5
	v_exp_f32_e32 v5, v5
	v_exp_f32_e32 v9, v7
	v_sub_f32_e32 v7, v32, v174
	v_mul_f32_e32 v7, 0x3fb8aa3b, v7
	v_exp_f32_e32 v16, v7
	v_sub_f32_e32 v7, v33, v174
	v_mul_f32_e32 v7, 0x3fb8aa3b, v7
	v_add_f32_e32 v6, v5, v6
	v_exp_f32_e32 v17, v7
	v_add_f32_e32 v6, v8, v6
	v_add_f32_e32 v6, v9, v6
	v_add_f32_e32 v6, v16, v6
	v_add_f32_e32 v7, v17, v6
	v_sub_f32_e32 v6, v34, v174
	v_mul_f32_e32 v6, 0x3fb8aa3b, v6
	v_exp_f32_e32 v6, v6
	v_sub_f32_e32 v15, v38, v174
	v_mul_f32_e32 v15, 0x3fb8aa3b, v15
	v_exp_f32_e32 v30, v15
	v_add_f32_e32 v12, v6, v7
	v_sub_f32_e32 v7, v35, v174
	v_mul_f32_e32 v7, 0x3fb8aa3b, v7
	v_exp_f32_e32 v7, v7
	v_sub_f32_e32 v15, v39, v174
	v_mul_f32_e32 v15, 0x3fb8aa3b, v15
	v_exp_f32_e32 v31, v15
	v_add_f32_e32 v13, v7, v12
	v_sub_f32_e32 v12, v36, v174
	v_mul_f32_e32 v12, 0x3fb8aa3b, v12
	v_exp_f32_e32 v12, v12
	v_sub_f32_e32 v15, v40, v174
	v_mul_f32_e32 v15, 0x3fb8aa3b, v15
	v_exp_f32_e32 v36, v15
	v_add_f32_e32 v14, v12, v13
	v_sub_f32_e32 v13, v37, v174
	v_mul_f32_e32 v13, 0x3fb8aa3b, v13
	v_exp_f32_e32 v13, v13
	v_sub_f32_e32 v15, v41, v174
	v_mul_f32_e32 v15, 0x3fb8aa3b, v15
	v_exp_f32_e32 v37, v15
	v_add_f32_e32 v14, v13, v14
	v_add_f32_e32 v14, v30, v14
	v_add_f32_e32 v14, v31, v14
	v_add_f32_e32 v14, v36, v14
	v_add_f32_e32 v15, v37, v14
	v_sub_f32_e32 v14, v42, v174
	v_mul_f32_e32 v14, 0x3fb8aa3b, v14
	v_exp_f32_e32 v14, v14
	v_sub_f32_e32 v35, v46, v174
	v_mul_f32_e32 v35, 0x3fb8aa3b, v35
	v_exp_f32_e32 v38, v35
	v_add_f32_e32 v32, v14, v15
	v_sub_f32_e32 v15, v43, v174
	v_mul_f32_e32 v15, 0x3fb8aa3b, v15
	v_exp_f32_e32 v15, v15
	v_sub_f32_e32 v35, v47, v174
	v_mul_f32_e32 v35, 0x3fb8aa3b, v35
	v_exp_f32_e32 v39, v35
	v_add_f32_e32 v33, v15, v32
	v_sub_f32_e32 v32, v44, v174
	v_mul_f32_e32 v32, 0x3fb8aa3b, v32
	v_exp_f32_e32 v32, v32
	v_sub_f32_e32 v35, v48, v174
	v_mul_f32_e32 v35, 0x3fb8aa3b, v35
	v_exp_f32_e32 v44, v35
	v_add_f32_e32 v34, v32, v33
	v_sub_f32_e32 v33, v45, v174
	v_mul_f32_e32 v33, 0x3fb8aa3b, v33
	v_exp_f32_e32 v33, v33
	v_sub_f32_e32 v35, v49, v174
	v_mul_f32_e32 v35, 0x3fb8aa3b, v35
	v_exp_f32_e32 v45, v35
	v_add_f32_e32 v34, v33, v34
	v_add_f32_e32 v34, v38, v34
	v_add_f32_e32 v34, v39, v34
	v_add_f32_e32 v34, v44, v34
	v_add_f32_e32 v35, v45, v34
	v_sub_f32_e32 v34, v50, v174
	v_mul_f32_e32 v34, 0x3fb8aa3b, v34
	v_exp_f32_e32 v34, v34
	v_sub_f32_e32 v43, v54, v174
	v_mul_f32_e32 v43, 0x3fb8aa3b, v43
	v_exp_f32_e32 v46, v43
	v_add_f32_e32 v40, v34, v35
	v_sub_f32_e32 v35, v51, v174
	v_mul_f32_e32 v35, 0x3fb8aa3b, v35
	v_exp_f32_e32 v35, v35
	v_sub_f32_e32 v43, v55, v174
	v_mul_f32_e32 v43, 0x3fb8aa3b, v43
	v_exp_f32_e32 v47, v43
	v_add_f32_e32 v41, v35, v40
	v_sub_f32_e32 v40, v52, v174
	v_mul_f32_e32 v40, 0x3fb8aa3b, v40
	v_exp_f32_e32 v40, v40
	v_sub_f32_e32 v43, v164, v174
	v_mul_f32_e32 v43, 0x3fb8aa3b, v43
	v_exp_f32_e32 v50, v43
	v_add_f32_e32 v42, v40, v41
	v_sub_f32_e32 v41, v53, v174
	v_mul_f32_e32 v41, 0x3fb8aa3b, v41
	v_exp_f32_e32 v41, v41
	v_sub_f32_e32 v43, v165, v174
	v_mul_f32_e32 v43, 0x3fb8aa3b, v43
	v_exp_f32_e32 v51, v43
	v_add_f32_e32 v42, v41, v42
	v_add_f32_e32 v42, v46, v42
	v_add_f32_e32 v42, v47, v42
	v_add_f32_e32 v42, v50, v42
	v_add_f32_e32 v43, v51, v42
	v_sub_f32_e32 v42, v166, v174
	v_mul_f32_e32 v42, 0x3fb8aa3b, v42
	v_exp_f32_e32 v42, v42
	v_sub_f32_e32 v163, v163, v174
	v_mul_f32_e32 v163, 0x3fb8aa3b, v163
	v_exp_f32_e32 v163, v163
	v_add_f32_e32 v48, v42, v43
	v_sub_f32_e32 v43, v167, v174
	v_mul_f32_e32 v43, 0x3fb8aa3b, v43
	v_exp_f32_e32 v43, v43
	s_nop 0
	v_add_f32_e32 v49, v43, v48
	v_sub_f32_e32 v48, v168, v174
	v_mul_f32_e32 v48, 0x3fb8aa3b, v48
	v_exp_f32_e32 v48, v48
	s_nop 0
	v_add_f32_e32 v52, v48, v49
	v_sub_f32_e32 v49, v169, v174
	v_mul_f32_e32 v49, 0x3fb8aa3b, v49
	v_exp_f32_e32 v49, v49
	s_nop 0
	v_add_f32_e32 v53, v49, v52
	v_sub_f32_e32 v52, v170, v174
	v_mul_f32_e32 v52, 0x3fb8aa3b, v52
	v_exp_f32_e32 v52, v52
	s_nop 0
	v_add_f32_e32 v54, v52, v53
	v_sub_f32_e32 v53, v171, v174
	v_mul_f32_e32 v53, 0x3fb8aa3b, v53
	v_exp_f32_e32 v53, v53
	s_nop 0
	v_add_f32_e32 v55, v53, v54
	v_sub_f32_e32 v54, v172, v174
	v_mul_f32_e32 v54, 0x3fb8aa3b, v54
	v_exp_f32_e32 v54, v54
	s_nop 0
	v_add_f32_e32 v164, v54, v55
	v_sub_f32_e32 v55, v173, v174
	v_mul_f32_e32 v55, 0x3fb8aa3b, v55
	v_exp_f32_e32 v55, v55
	s_nop 0
	v_add_f32_e32 v164, v55, v164
	ds_swizzle_b32 v165, v164 offset:swizzle(SWAP,16)
	s_waitcnt lgkmcnt(0)
	v_add_f32_e32 v164, v164, v165
	ds_bpermute_b32 v165, v19, v164
	s_waitcnt lgkmcnt(0)
	v_add_f32_e32 v164, v164, v165
	v_add_f32_e32 v163, v163, v164
	v_div_scale_f32 v164, s[2:3], v163, v163, 1.0
	v_rcp_f32_e32 v165, v164
	s_nop 0
	v_fma_f32 v166, -v164, v165, 1.0
	v_fmac_f32_e32 v165, v166, v165
	v_div_scale_f32 v166, vcc, 1.0, v163, 1.0
	v_mul_f32_e32 v167, v166, v165
	v_fma_f32 v168, -v164, v167, v166
	v_fmac_f32_e32 v167, v168, v165
	v_fma_f32 v164, -v164, v167, v166
	v_div_fmas_f32 v164, v164, v165, v167
	v_div_fixup_f32 v180, v164, v163, 1.0
	v_mul_f32_e32 v4, v180, v4
	v_mul_f32_e32 v5, v180, v5
	v_mul_f32_e32 v2, v180, v2
	v_mul_f32_e32 v3, v180, v3
	v_mul_f32_e32 v16, v180, v16
	v_mul_f32_e32 v17, v180, v17
	v_mul_f32_e32 v8, v180, v8
	v_mul_f32_e32 v9, v180, v9
	v_cvt_pk_bf16_f32 v2, v2, v3
	v_cvt_pk_bf16_f32 v3, v4, v5
	v_mul_f32_e32 v6, v180, v6
	v_mul_f32_e32 v7, v180, v7
	v_cvt_pk_bf16_f32 v4, v8, v9
	v_cvt_pk_bf16_f32 v5, v16, v17
	ds_read2_b64 v[164:167], v137 offset1:4
	ds_read2_b64 v[168:171], v138 offset0:32 offset1:36
	ds_read2_b64 v[172:175], v139 offset0:64 offset1:68
	ds_read2_b64 v[176:179], v140 offset0:96 offset1:100
	v_mul_f32_e32 v8, v180, v12
	v_mul_f32_e32 v9, v180, v13
	s_waitcnt lgkmcnt(3)
	v_mfma_f32_16x16x32_bf16 v[164:167], v[164:167], v[2:5], 0
	v_mul_f32_e64 v12, v36, v180
	v_mul_f32_e64 v13, v37, v180
	v_mul_f32_e32 v16, v180, v30
	v_mul_f32_e32 v17, v180, v31
	v_cvt_pk_bf16_f32 v6, v6, v7
	s_waitcnt lgkmcnt(2)
	v_mfma_f32_16x16x32_bf16 v[168:171], v[168:171], v[2:5], 0
	v_cvt_pk_bf16_f32 v7, v8, v9
	v_cvt_pk_bf16_f32 v8, v16, v17
	v_cvt_pk_bf16_f32 v9, v12, v13
	s_waitcnt lgkmcnt(1)
	v_mfma_f32_16x16x32_bf16 v[172:175], v[172:175], v[2:5], 0
	v_mul_f32_e64 v12, v44, v180
	v_mul_f32_e64 v13, v45, v180
	v_mul_f32_e32 v16, v180, v50
	v_mul_f32_e32 v17, v180, v51
	s_waitcnt lgkmcnt(0)
	v_mfma_f32_16x16x32_bf16 v[2:5], v[176:179], v[2:5], 0
	ds_read2_b64 v[176:179], v58 offset1:4
	s_waitcnt lgkmcnt(0)
	v_mfma_f32_16x16x32_bf16 v[164:167], v[176:179], v[6:9], v[164:167]
	ds_read2_b64 v[176:179], v59 offset0:32 offset1:36
	s_waitcnt lgkmcnt(0)
	v_mfma_f32_16x16x32_bf16 v[168:171], v[176:179], v[6:9], v[168:171]
	ds_read2_b64 v[176:179], v60 offset0:64 offset1:68
	ds_read2_b64 v[58:61], v61 offset0:96 offset1:100
	s_waitcnt lgkmcnt(1)
	v_mfma_f32_16x16x32_bf16 v[172:175], v[176:179], v[6:9], v[172:175]
	s_waitcnt lgkmcnt(0)
	v_mfma_f32_16x16x32_bf16 v[2:5], v[58:61], v[6:9], v[2:5]
	v_mul_f32_e64 v8, v32, v180
	v_mul_f32_e64 v9, v33, v180
	v_mul_f32_e32 v6, v180, v14
	v_mul_f32_e32 v7, v180, v15
	v_mul_f32_e32 v14, v180, v38
	v_mul_f32_e32 v15, v180, v39
	v_cvt_pk_bf16_f32 v6, v6, v7
	v_cvt_pk_bf16_f32 v7, v8, v9
	s_nop 0
	v_cvt_pk_bf16_f32 v8, v14, v15
	v_cvt_pk_bf16_f32 v9, v12, v13
	ds_read2_b64 v[12:15], v56 offset1:4
	ds_read2_b64 v[30:33], v57 offset0:32 offset1:36
	ds_read2_b64 v[36:39], v62 offset0:64 offset1:68
	ds_read2_b64 v[56:59], v63 offset0:96 offset1:100
	s_waitcnt lgkmcnt(3)
	v_mfma_f32_16x16x32_bf16 v[12:15], v[12:15], v[6:9], v[164:167]
	s_waitcnt lgkmcnt(2)
	v_mfma_f32_16x16x32_bf16 v[30:33], v[30:33], v[6:9], v[168:171]
	s_waitcnt lgkmcnt(1)
	v_mfma_f32_16x16x32_bf16 v[36:39], v[36:39], v[6:9], v[172:175]
	s_waitcnt lgkmcnt(0)
	v_mfma_f32_16x16x32_bf16 v[2:5], v[56:59], v[6:9], v[2:5]
	v_mul_f32_e64 v8, v40, v180
	v_mul_f32_e64 v9, v41, v180
	v_mul_f32_e32 v6, v180, v34
	v_mul_f32_e32 v7, v180, v35
	v_mul_f32_e32 v34, v180, v46
	v_mul_f32_e32 v35, v180, v47
	v_cvt_pk_bf16_f32 v6, v6, v7
	v_cvt_pk_bf16_f32 v7, v8, v9
	s_nop 0
	v_cvt_pk_bf16_f32 v8, v34, v35
	v_cvt_pk_bf16_f32 v9, v16, v17
	ds_read2_b64 v[44:47], v64 offset1:4
	s_waitcnt lgkmcnt(0)
	v_mfma_f32_16x16x32_bf16 v[12:15], v[44:47], v[6:9], v[12:15]
	ds_read2_b64 v[44:47], v65 offset0:32 offset1:36
	v_mul_f32_e32 v16, v180, v54
	v_mul_f32_e32 v17, v180, v55
	s_waitcnt lgkmcnt(0)
	v_mfma_f32_16x16x32_bf16 v[30:33], v[44:47], v[6:9], v[30:33]
	ds_read2_b64 v[44:47], v141 offset0:64 offset1:68
	s_waitcnt lgkmcnt(0)
	v_mfma_f32_16x16x32_bf16 v[34:37], v[44:47], v[6:9], v[36:39]
	s_nop 2
	ds_read2_b64 v[38:41], v142 offset0:96 offset1:100
	s_waitcnt lgkmcnt(0)
	v_mfma_f32_16x16x32_bf16 v[2:5], v[38:41], v[6:9], v[2:5]
	v_mul_f32_e64 v8, v48, v180
	v_mul_f32_e64 v9, v49, v180
	v_mul_f32_e32 v6, v180, v42
	v_mul_f32_e32 v7, v180, v43
	v_mul_f32_e32 v38, v180, v52
	v_mul_f32_e32 v39, v180, v53
	v_cvt_pk_bf16_f32 v6, v6, v7
	v_cvt_pk_bf16_f32 v7, v8, v9
	s_nop 0
	v_cvt_pk_bf16_f32 v8, v38, v39
	v_cvt_pk_bf16_f32 v9, v16, v17
	ds_read2_b64 v[38:41], v143 offset1:4
	s_waitcnt lgkmcnt(0)
	v_mfma_f32_16x16x32_bf16 v[12:15], v[38:41], v[6:9], v[12:15]
	ds_read2_b64 v[38:41], v144 offset0:32 offset1:36
	s_waitcnt lgkmcnt(0)
	v_mfma_f32_16x16x32_bf16 v[30:33], v[38:41], v[6:9], v[30:33]
	ds_read2_b64 v[38:41], v145 offset0:64 offset1:68
	s_waitcnt lgkmcnt(0)
	v_mfma_f32_16x16x32_bf16 v[34:37], v[38:41], v[6:9], v[34:37]
	ds_read2_b64 v[38:41], v162 offset0:96 offset1:100
	s_waitcnt lgkmcnt(0)
	v_mfma_f32_16x16x32_bf16 v[2:5], v[38:41], v[6:9], v[2:5]
	v_lshl_add_u64 v[6:7], v[10:11], 0, s[88:89]
	v_cvt_pk_bf16_f32 v8, v12, v13
	v_cvt_pk_bf16_f32 v9, v14, v15
	global_store_dwordx2 v[6:7], v[8:9], off
	v_cvt_pk_bf16_f32 v8, v30, v31
	v_cvt_pk_bf16_f32 v9, v32, v33
	global_store_dwordx2 v[6:7], v[8:9], off offset:32
	v_cvt_pk_bf16_f32 v8, v34, v35
	v_cvt_pk_bf16_f32 v9, v36, v37
	global_store_dwordx2 v[6:7], v[8:9], off offset:64
	v_cvt_pk_bf16_f32 v2, v2, v3
	v_cvt_pk_bf16_f32 v3, v4, v5
	s_nop 3
	global_store_dwordx2 v[6:7], v[2:3], off offset:96
	s_cbranch_scc0 .LBB0_115
